# batched residual-GEMM epilogues (BM=256: 8 loads per wait; tail BM=128: 4 loads per wait)
# speedup vs baseline: 1.2090x; 1.0010x over previous
;     ...
;   for (int it = 0;; it++) {
;     int tile;
;     if (nb == 512) tile = ((it * 8 + (bid & 7)) << 6) + (bid >> 3); else tile = it * nb + bid;
;     tile += tbeg;
;     if (tile >= MTX * ntn || tile >= tend) break;
;     ...
;             if constexpr (EPI == EPI_RESID) {
;               if (pr >= PADR) {
;                 float4* hp = (float4*)(e.f0 + (row * (unsigned)D + col));
;                 float4 hv = *hp;
;                 hv.x += e.alpha * a[0]; hv.y += e.alpha * a[1]; hv.z += e.alpha * a[2]; hv.w += e.alpha * a[3];
;                 *hp = hv;
;               }
.LBB0_2571:
.Lre_latch:
	s_add_i32 s16, s16, 1
	s_lshl_b32 s2, s16, 9
	s_add_i32 s2, s2, s13
	s_cmpk_lt_i32 s2, 0x400
	s_cbranch_scc0 .LBB0_2590

;     ...
;       const unsigned rb2 = (unsigned)(m0 + wm * (BM / 2) + fr);
;       const unsigned cb2 = (unsigned)(n0 + wn * 64 + fq * 4);
; #pragma unroll
;       for (int mi = 0; mi < MI; mi++) {
;         const unsigned row = rb2 + mi * 16;
;         const unsigned pr = row % (unsigned)LP;
;     ...
;           for (int ni = 0; ni < 4; ni++) {
;             const unsigned col = cb2 + ni * 16;
;             const f32x4 a = acc[mi][ni];
;             if constexpr (EPI == EPI_RESID) {
;               if (pr >= PADR) {
;                 float4* hp = (float4*)(e.f0 + (row * (unsigned)D + col));
;                 float4 hv = *hp;
;                 hv.x += e.alpha * a[0]; hv.y += e.alpha * a[1]; hv.z += e.alpha * a[2]; hv.w += e.alpha * a[3];
;                 *hp = hv;
;               }
.LBB0_2575:
	v_add_u32_e32 v202, s17, v152
	v_or_b32_e32 v203, s18, v153
	v_readlane_b32 s22, v247, 3
	v_readlane_b32 s23, v247, 4
	v_readlane_b32 s20, v244, 15
	v_readlane_b32 s21, v244, 16
	s_mov_b32 s2, 0xfc0fc0fd
	s_movk_i32 s19, 0x6f
	v_mov_b32_e32 v204, v202
	v_mul_hi_u32 v226, v204, s2
	v_lshl_add_u32 v8, v204, 10, v203
	v_lshrrev_b32_e32 v226, 13, v226
	v_lshl_add_u64 v[198:199], v[8:9], 2, s[22:23]
	v_mul_u32_u24_e32 v226, 0x2080, v226
	v_sub_u32_e32 v226, v204, v226
	v_cmp_lt_u32_e64 s[24:25], s19, v226
	v_add_u32_e32 v205, 16, v202
	v_mul_hi_u32 v227, v205, s2
	v_lshl_add_u32 v8, v205, 10, v203
	v_lshrrev_b32_e32 v227, 13, v227
	v_lshl_add_u64 v[200:201], v[8:9], 2, s[22:23]
	v_mul_u32_u24_e32 v227, 0x2080, v227
	v_sub_u32_e32 v227, v205, v227
	v_cmp_lt_u32_e64 s[26:27], s19, v227
	s_mov_b64 exec, s[24:25]
	global_load_dwordx4 v[166:169], v[198:199], off
	global_load_dwordx4 v[170:173], v[198:199], off offset:64
	global_load_dwordx4 v[174:177], v[198:199], off offset:128
	global_load_dwordx4 v[178:181], v[198:199], off offset:192
	s_mov_b64 exec, s[26:27]
	global_load_dwordx4 v[182:185], v[200:201], off
	global_load_dwordx4 v[186:189], v[200:201], off offset:64
	global_load_dwordx4 v[190:193], v[200:201], off offset:128
	global_load_dwordx4 v[194:197], v[200:201], off offset:192
	s_mov_b64 exec, -1
	s_waitcnt vmcnt(0)
	v_pk_fma_f32 v[134:135], s[20:21], v[134:135], v[166:167]
	v_pk_fma_f32 v[136:137], s[20:21], v[136:137], v[168:169]
	v_pk_fma_f32 v[130:131], s[20:21], v[130:131], v[170:171]
	v_pk_fma_f32 v[132:133], s[20:21], v[132:133], v[172:173]
	v_pk_fma_f32 v[126:127], s[20:21], v[126:127], v[174:175]
	v_pk_fma_f32 v[128:129], s[20:21], v[128:129], v[176:177]
	v_pk_fma_f32 v[122:123], s[20:21], v[122:123], v[178:179]
	v_pk_fma_f32 v[124:125], s[20:21], v[124:125], v[180:181]
	v_pk_fma_f32 v[118:119], s[20:21], v[118:119], v[182:183]
	v_pk_fma_f32 v[120:121], s[20:21], v[120:121], v[184:185]
	v_pk_fma_f32 v[114:115], s[20:21], v[114:115], v[186:187]
	v_pk_fma_f32 v[116:117], s[20:21], v[116:117], v[188:189]
	v_pk_fma_f32 v[110:111], s[20:21], v[110:111], v[190:191]
	v_pk_fma_f32 v[112:113], s[20:21], v[112:113], v[192:193]
	v_pk_fma_f32 v[106:107], s[20:21], v[106:107], v[194:195]
	v_pk_fma_f32 v[108:109], s[20:21], v[108:109], v[196:197]
	s_mov_b64 exec, s[24:25]
	global_store_dwordx4 v[198:199], v[134:137], off
	global_store_dwordx4 v[198:199], v[130:133], off offset:64
	global_store_dwordx4 v[198:199], v[126:129], off offset:128
	global_store_dwordx4 v[198:199], v[122:125], off offset:192
	s_mov_b64 exec, s[26:27]
	global_store_dwordx4 v[200:201], v[118:121], off
	global_store_dwordx4 v[200:201], v[114:117], off offset:64
	global_store_dwordx4 v[200:201], v[110:113], off offset:128
	global_store_dwordx4 v[200:201], v[106:109], off offset:192
	s_mov_b64 exec, -1
	v_add_u32_e32 v204, 32, v202
	v_mul_hi_u32 v226, v204, s2
	v_lshl_add_u32 v8, v204, 10, v203
	v_lshrrev_b32_e32 v226, 13, v226
	v_lshl_add_u64 v[198:199], v[8:9], 2, s[22:23]
	v_mul_u32_u24_e32 v226, 0x2080, v226
	v_sub_u32_e32 v226, v204, v226
	v_cmp_lt_u32_e64 s[24:25], s19, v226
	v_add_u32_e32 v205, 48, v202
	v_mul_hi_u32 v227, v205, s2
	v_lshl_add_u32 v8, v205, 10, v203
	v_lshrrev_b32_e32 v227, 13, v227
	v_lshl_add_u64 v[200:201], v[8:9], 2, s[22:23]
	v_mul_u32_u24_e32 v227, 0x2080, v227
	v_sub_u32_e32 v227, v205, v227
	v_cmp_lt_u32_e64 s[26:27], s19, v227
	s_mov_b64 exec, s[24:25]
	global_load_dwordx4 v[166:169], v[198:199], off
	global_load_dwordx4 v[170:173], v[198:199], off offset:64
	global_load_dwordx4 v[174:177], v[198:199], off offset:128
	global_load_dwordx4 v[178:181], v[198:199], off offset:192
	s_mov_b64 exec, s[26:27]
	global_load_dwordx4 v[182:185], v[200:201], off
	global_load_dwordx4 v[186:189], v[200:201], off offset:64
	global_load_dwordx4 v[190:193], v[200:201], off offset:128
	global_load_dwordx4 v[194:197], v[200:201], off offset:192
	s_mov_b64 exec, -1
	s_waitcnt vmcnt(0)
;     ...
;           for (int ni = 0; ni < 4; ni++) {
;             const unsigned col = cb2 + ni * 16;
;             const f32x4 a = acc[mi][ni];
;             if constexpr (EPI == EPI_RESID) {
;               if (pr >= PADR) {
;                 float4* hp = (float4*)(e.f0 + (row * (unsigned)D + col));
;                 float4 hv = *hp;
;                 hv.x += e.alpha * a[0]; hv.y += e.alpha * a[1]; hv.z += e.alpha * a[2]; hv.w += e.alpha * a[3];
;                 *hp = hv;
;               }
	v_pk_fma_f32 v[102:103], s[20:21], v[102:103], v[166:167]
	v_pk_fma_f32 v[104:105], s[20:21], v[104:105], v[168:169]
	v_pk_fma_f32 v[98:99], s[20:21], v[98:99], v[170:171]
	v_pk_fma_f32 v[100:101], s[20:21], v[100:101], v[172:173]
	v_pk_fma_f32 v[94:95], s[20:21], v[94:95], v[174:175]
	v_pk_fma_f32 v[96:97], s[20:21], v[96:97], v[176:177]
	v_pk_fma_f32 v[90:91], s[20:21], v[90:91], v[178:179]
	v_pk_fma_f32 v[92:93], s[20:21], v[92:93], v[180:181]
	v_pk_fma_f32 v[86:87], s[20:21], v[86:87], v[182:183]
	v_pk_fma_f32 v[88:89], s[20:21], v[88:89], v[184:185]
	v_pk_fma_f32 v[82:83], s[20:21], v[82:83], v[186:187]
	v_pk_fma_f32 v[84:85], s[20:21], v[84:85], v[188:189]
	v_pk_fma_f32 v[78:79], s[20:21], v[78:79], v[190:191]
	v_pk_fma_f32 v[80:81], s[20:21], v[80:81], v[192:193]
	v_pk_fma_f32 v[74:75], s[20:21], v[74:75], v[194:195]
	v_pk_fma_f32 v[76:77], s[20:21], v[76:77], v[196:197]
	s_mov_b64 exec, s[24:25]
	global_store_dwordx4 v[198:199], v[102:105], off
	global_store_dwordx4 v[198:199], v[98:101], off offset:64
	global_store_dwordx4 v[198:199], v[94:97], off offset:128
	global_store_dwordx4 v[198:199], v[90:93], off offset:192
	s_mov_b64 exec, s[26:27]
	global_store_dwordx4 v[200:201], v[86:89], off
	global_store_dwordx4 v[200:201], v[82:85], off offset:64
	global_store_dwordx4 v[200:201], v[78:81], off offset:128
	global_store_dwordx4 v[200:201], v[74:77], off offset:192
	s_mov_b64 exec, -1
	v_add_u32_e32 v204, 64, v202
	v_mul_hi_u32 v226, v204, s2
	v_lshl_add_u32 v8, v204, 10, v203
	v_lshrrev_b32_e32 v226, 13, v226
	v_lshl_add_u64 v[198:199], v[8:9], 2, s[22:23]
	v_mul_u32_u24_e32 v226, 0x2080, v226
	v_sub_u32_e32 v226, v204, v226
	v_cmp_lt_u32_e64 s[24:25], s19, v226
	v_add_u32_e32 v205, 80, v202
	v_mul_hi_u32 v227, v205, s2
	v_lshl_add_u32 v8, v205, 10, v203
	v_lshrrev_b32_e32 v227, 13, v227
	v_lshl_add_u64 v[200:201], v[8:9], 2, s[22:23]
	v_mul_u32_u24_e32 v227, 0x2080, v227
	v_sub_u32_e32 v227, v205, v227
	v_cmp_lt_u32_e64 s[26:27], s19, v227
	s_mov_b64 exec, s[24:25]
	global_load_dwordx4 v[166:169], v[198:199], off
	global_load_dwordx4 v[170:173], v[198:199], off offset:64
	global_load_dwordx4 v[174:177], v[198:199], off offset:128
	global_load_dwordx4 v[178:181], v[198:199], off offset:192
	s_mov_b64 exec, s[26:27]
	global_load_dwordx4 v[182:185], v[200:201], off
	global_load_dwordx4 v[186:189], v[200:201], off offset:64
	global_load_dwordx4 v[190:193], v[200:201], off offset:128
	global_load_dwordx4 v[194:197], v[200:201], off offset:192
	s_mov_b64 exec, -1
	s_waitcnt vmcnt(0)
	v_pk_fma_f32 v[70:71], s[20:21], v[70:71], v[166:167]
	v_pk_fma_f32 v[72:73], s[20:21], v[72:73], v[168:169]
	v_pk_fma_f32 v[66:67], s[20:21], v[66:67], v[170:171]
	v_pk_fma_f32 v[68:69], s[20:21], v[68:69], v[172:173]
	v_pk_fma_f32 v[62:63], s[20:21], v[62:63], v[174:175]
	v_pk_fma_f32 v[64:65], s[20:21], v[64:65], v[176:177]
	v_pk_fma_f32 v[58:59], s[20:21], v[58:59], v[178:179]
	v_pk_fma_f32 v[60:61], s[20:21], v[60:61], v[180:181]
	v_pk_fma_f32 v[54:55], s[20:21], v[54:55], v[182:183]
	v_pk_fma_f32 v[56:57], s[20:21], v[56:57], v[184:185]
	v_pk_fma_f32 v[50:51], s[20:21], v[50:51], v[186:187]
	v_pk_fma_f32 v[52:53], s[20:21], v[52:53], v[188:189]
	v_pk_fma_f32 v[46:47], s[20:21], v[46:47], v[190:191]
	v_pk_fma_f32 v[48:49], s[20:21], v[48:49], v[192:193]
	v_pk_fma_f32 v[42:43], s[20:21], v[42:43], v[194:195]
	v_pk_fma_f32 v[44:45], s[20:21], v[44:45], v[196:197]
	s_mov_b64 exec, s[24:25]
	global_store_dwordx4 v[198:199], v[70:73], off
	global_store_dwordx4 v[198:199], v[66:69], off offset:64
	global_store_dwordx4 v[198:199], v[62:65], off offset:128
	global_store_dwordx4 v[198:199], v[58:61], off offset:192
	s_mov_b64 exec, s[26:27]
	global_store_dwordx4 v[200:201], v[54:57], off
	global_store_dwordx4 v[200:201], v[50:53], off offset:64
	global_store_dwordx4 v[200:201], v[46:49], off offset:128
	global_store_dwordx4 v[200:201], v[42:45], off offset:192
	s_mov_b64 exec, -1
	v_add_u32_e32 v204, 96, v202
	v_mul_hi_u32 v226, v204, s2
	v_lshl_add_u32 v8, v204, 10, v203
	v_lshrrev_b32_e32 v226, 13, v226
	v_lshl_add_u64 v[198:199], v[8:9], 2, s[22:23]
	v_mul_u32_u24_e32 v226, 0x2080, v226
	v_sub_u32_e32 v226, v204, v226
	v_cmp_lt_u32_e64 s[24:25], s19, v226
	v_add_u32_e32 v205, 112, v202
	v_mul_hi_u32 v227, v205, s2
	v_lshl_add_u32 v8, v205, 10, v203
	v_lshrrev_b32_e32 v227, 13, v227
	v_lshl_add_u64 v[200:201], v[8:9], 2, s[22:23]
	v_mul_u32_u24_e32 v227, 0x2080, v227
	v_sub_u32_e32 v227, v205, v227
	v_cmp_lt_u32_e64 s[26:27], s19, v227
	s_mov_b64 exec, s[24:25]
	global_load_dwordx4 v[166:169], v[198:199], off
	global_load_dwordx4 v[170:173], v[198:199], off offset:64
	global_load_dwordx4 v[174:177], v[198:199], off offset:128
	global_load_dwordx4 v[178:181], v[198:199], off offset:192
	s_mov_b64 exec, s[26:27]
	global_load_dwordx4 v[182:185], v[200:201], off
	global_load_dwordx4 v[186:189], v[200:201], off offset:64
	global_load_dwordx4 v[190:193], v[200:201], off offset:128
	global_load_dwordx4 v[194:197], v[200:201], off offset:192
	s_mov_b64 exec, -1
	s_waitcnt vmcnt(0)
	v_pk_fma_f32 v[38:39], s[20:21], v[38:39], v[166:167]
	v_pk_fma_f32 v[40:41], s[20:21], v[40:41], v[168:169]
	v_pk_fma_f32 v[34:35], s[20:21], v[34:35], v[170:171]
	v_pk_fma_f32 v[36:37], s[20:21], v[36:37], v[172:173]
	v_pk_fma_f32 v[30:31], s[20:21], v[30:31], v[174:175]
	v_pk_fma_f32 v[32:33], s[20:21], v[32:33], v[176:177]
	v_pk_fma_f32 v[26:27], s[20:21], v[26:27], v[178:179]
	v_pk_fma_f32 v[28:29], s[20:21], v[28:29], v[180:181]
	v_pk_fma_f32 v[22:23], s[20:21], v[22:23], v[182:183]
	v_pk_fma_f32 v[24:25], s[20:21], v[24:25], v[184:185]
	v_pk_fma_f32 v[18:19], s[20:21], v[18:19], v[186:187]
	v_pk_fma_f32 v[20:21], s[20:21], v[20:21], v[188:189]
	v_pk_fma_f32 v[14:15], s[20:21], v[14:15], v[190:191]
	v_pk_fma_f32 v[16:17], s[20:21], v[16:17], v[192:193]
	v_pk_fma_f32 v[10:11], s[20:21], v[10:11], v[194:195]
	v_pk_fma_f32 v[12:13], s[20:21], v[12:13], v[196:197]
	s_mov_b64 exec, s[24:25]
	global_store_dwordx4 v[198:199], v[38:41], off
	global_store_dwordx4 v[198:199], v[34:37], off offset:64
	global_store_dwordx4 v[198:199], v[30:33], off offset:128
	global_store_dwordx4 v[198:199], v[26:29], off offset:192
	s_mov_b64 exec, s[26:27]
	global_store_dwordx4 v[200:201], v[22:25], off
	global_store_dwordx4 v[200:201], v[18:21], off offset:64
	global_store_dwordx4 v[200:201], v[14:17], off offset:128
	global_store_dwordx4 v[200:201], v[10:13], off offset:192
	s_mov_b64 exec, -1
	s_branch .Lre_latch

;     ...
;       const unsigned rb2 = (unsigned)(m0 + wm * (BM / 2) + fr);
;       const unsigned cb2 = (unsigned)(n0 + wn * 64 + fq * 4);
; #pragma unroll
;       for (int mi = 0; mi < MI; mi++) {
;         const unsigned row = rb2 + mi * 16;
;         const unsigned pr = row % (unsigned)LP;
;     ...
;           for (int ni = 0; ni < 4; ni++) {
;             const unsigned col = cb2 + ni * 16;
;             const f32x4 a = acc[mi][ni];
;             if constexpr (EPI == EPI_RESID) {
;               if (pr >= PADR) {
;                 float4* hp = (float4*)(e.f0 + (row * (unsigned)D + col));
;                 float4 hv = *hp;
;                 hv.x += e.alpha * a[0]; hv.y += e.alpha * a[1]; hv.z += e.alpha * a[2]; hv.w += e.alpha * a[3];
;                 *hp = hv;
;               }
.LBB0_2604:
	v_add_u32_e32 v79, s4, v96
	v_or_b32_e32 v78, s5, v97
	v_readlane_b32 s22, v247, 3
	v_readlane_b32 s23, v247, 4
	v_readlane_b32 s18, v244, 15
	v_readlane_b32 s19, v244, 16
	s_mov_b32 s2, 0xfc0fc0fd
	s_movk_i32 s20, 0x6f
	v_mov_b32_e32 v80, v79
	v_mul_hi_u32 v81, v80, s2
	v_lshl_add_u32 v8, v80, 10, v78
	v_lshrrev_b32_e32 v81, 13, v81
	v_lshl_add_u64 v[84:85], v[8:9], 2, s[22:23]
	v_mul_u32_u24_e32 v81, 0x2080, v81
	v_sub_u32_e32 v81, v80, v81
	v_cmp_lt_u32_e64 s[4:5], s20, v81
	s_nop 1
	s_mov_b64 exec, s[4:5]
	global_load_dwordx4 v[228:231], v[84:85], off
	global_load_dwordx4 v[232:235], v[84:85], off offset:64
	global_load_dwordx4 v[236:239], v[84:85], off offset:128
	global_load_dwordx4 v[240:243], v[84:85], off offset:192
	s_waitcnt vmcnt(0)
	v_pk_fma_f32 v[70:71], s[18:19], v[70:71], v[228:229]
	v_pk_fma_f32 v[72:73], s[18:19], v[72:73], v[230:231]
	v_pk_fma_f32 v[66:67], s[18:19], v[66:67], v[232:233]
	v_pk_fma_f32 v[68:69], s[18:19], v[68:69], v[234:235]
	v_pk_fma_f32 v[62:63], s[18:19], v[62:63], v[236:237]
	v_pk_fma_f32 v[64:65], s[18:19], v[64:65], v[238:239]
	v_pk_fma_f32 v[58:59], s[18:19], v[58:59], v[240:241]
	v_pk_fma_f32 v[60:61], s[18:19], v[60:61], v[242:243]
	global_store_dwordx4 v[84:85], v[70:73], off
	global_store_dwordx4 v[84:85], v[66:69], off offset:64
	global_store_dwordx4 v[84:85], v[62:65], off offset:128
	global_store_dwordx4 v[84:85], v[58:61], off offset:192
	s_mov_b64 exec, -1
	v_add_u32_e32 v80, 16, v79
	v_mul_hi_u32 v81, v80, s2
	v_lshl_add_u32 v8, v80, 10, v78
	v_lshrrev_b32_e32 v81, 13, v81
	v_lshl_add_u64 v[84:85], v[8:9], 2, s[22:23]
	v_mul_u32_u24_e32 v81, 0x2080, v81
	v_sub_u32_e32 v81, v80, v81
	v_cmp_lt_u32_e64 s[4:5], s20, v81
	s_nop 1
	s_mov_b64 exec, s[4:5]
	global_load_dwordx4 v[228:231], v[84:85], off
	global_load_dwordx4 v[232:235], v[84:85], off offset:64
	global_load_dwordx4 v[236:239], v[84:85], off offset:128
	global_load_dwordx4 v[240:243], v[84:85], off offset:192
	s_waitcnt vmcnt(0)
	v_pk_fma_f32 v[54:55], s[18:19], v[54:55], v[228:229]
	v_pk_fma_f32 v[56:57], s[18:19], v[56:57], v[230:231]
	v_pk_fma_f32 v[50:51], s[18:19], v[50:51], v[232:233]
	v_pk_fma_f32 v[52:53], s[18:19], v[52:53], v[234:235]
	v_pk_fma_f32 v[46:47], s[18:19], v[46:47], v[236:237]
	v_pk_fma_f32 v[48:49], s[18:19], v[48:49], v[238:239]
	v_pk_fma_f32 v[42:43], s[18:19], v[42:43], v[240:241]
	v_pk_fma_f32 v[44:45], s[18:19], v[44:45], v[242:243]
	global_store_dwordx4 v[84:85], v[54:57], off
	global_store_dwordx4 v[84:85], v[50:53], off offset:64
	global_store_dwordx4 v[84:85], v[46:49], off offset:128
	global_store_dwordx4 v[84:85], v[42:45], off offset:192
	s_mov_b64 exec, -1
	v_add_u32_e32 v80, 32, v79
	v_mul_hi_u32 v81, v80, s2
	v_lshl_add_u32 v8, v80, 10, v78
	v_lshrrev_b32_e32 v81, 13, v81
	v_lshl_add_u64 v[84:85], v[8:9], 2, s[22:23]
	v_mul_u32_u24_e32 v81, 0x2080, v81
	v_sub_u32_e32 v81, v80, v81
	v_cmp_lt_u32_e64 s[4:5], s20, v81
	s_nop 1
	s_mov_b64 exec, s[4:5]
	global_load_dwordx4 v[228:231], v[84:85], off
	global_load_dwordx4 v[232:235], v[84:85], off offset:64
	global_load_dwordx4 v[236:239], v[84:85], off offset:128
	global_load_dwordx4 v[240:243], v[84:85], off offset:192
	s_waitcnt vmcnt(0)
	v_pk_fma_f32 v[38:39], s[18:19], v[38:39], v[228:229]
	v_pk_fma_f32 v[40:41], s[18:19], v[40:41], v[230:231]
	v_pk_fma_f32 v[34:35], s[18:19], v[34:35], v[232:233]
	v_pk_fma_f32 v[36:37], s[18:19], v[36:37], v[234:235]
	v_pk_fma_f32 v[30:31], s[18:19], v[30:31], v[236:237]
	v_pk_fma_f32 v[32:33], s[18:19], v[32:33], v[238:239]
	v_pk_fma_f32 v[26:27], s[18:19], v[26:27], v[240:241]
	v_pk_fma_f32 v[28:29], s[18:19], v[28:29], v[242:243]
	global_store_dwordx4 v[84:85], v[38:41], off
	global_store_dwordx4 v[84:85], v[34:37], off offset:64
	global_store_dwordx4 v[84:85], v[30:33], off offset:128
	global_store_dwordx4 v[84:85], v[26:29], off offset:192
	s_mov_b64 exec, -1
	v_add_u32_e32 v80, 48, v79
	v_mul_hi_u32 v81, v80, s2
	v_lshl_add_u32 v8, v80, 10, v78
	v_lshrrev_b32_e32 v81, 13, v81
	v_lshl_add_u64 v[84:85], v[8:9], 2, s[22:23]
	v_mul_u32_u24_e32 v81, 0x2080, v81
	v_sub_u32_e32 v81, v80, v81
	v_cmp_lt_u32_e64 s[4:5], s20, v81
	s_nop 1
	s_mov_b64 exec, s[4:5]
	global_load_dwordx4 v[228:231], v[84:85], off
	global_load_dwordx4 v[232:235], v[84:85], off offset:64
	global_load_dwordx4 v[236:239], v[84:85], off offset:128
	global_load_dwordx4 v[240:243], v[84:85], off offset:192
	s_waitcnt vmcnt(0)
	v_pk_fma_f32 v[22:23], s[18:19], v[22:23], v[228:229]
	v_pk_fma_f32 v[24:25], s[18:19], v[24:25], v[230:231]
	v_pk_fma_f32 v[18:19], s[18:19], v[18:19], v[232:233]
	v_pk_fma_f32 v[20:21], s[18:19], v[20:21], v[234:235]
	v_pk_fma_f32 v[10:11], s[18:19], v[10:11], v[236:237]
	v_pk_fma_f32 v[12:13], s[18:19], v[12:13], v[238:239]
	v_pk_fma_f32 v[14:15], s[18:19], v[14:15], v[240:241]
	v_pk_fma_f32 v[16:17], s[18:19], v[16:17], v[242:243]
	global_store_dwordx4 v[84:85], v[22:25], off
	global_store_dwordx4 v[84:85], v[18:21], off offset:64
	global_store_dwordx4 v[84:85], v[10:13], off offset:128
	global_store_dwordx4 v[84:85], v[14:17], off offset:192
	s_mov_b64 exec, -1
	s_branch .LBB0_2594
